# combo2 + non-temporal hint on the up-GEMM U stores (keep H/W13 resident beyond L2 while U streams out)
# speedup vs baseline: 1.0111x; 1.0055x over previous
; __device__ __forceinline__ unsigned cvt_pk_bf16(float lo, float hi) { unsigned r; asm volatile("v_cvt_pk_bf16_f32 %0, %1, %2" : "=v"(r) : "v"(lo), "v"(hi)); return r; }
; __device__ __forceinline__ f32x2 silu_mul_pk(f32x2 a, f32x2 b) {
;     const f32x2 t = a * (-1.4426950408889634f); f32x2 e; e.x = __builtin_amdgcn_exp2f(t.x); e.y = __builtin_amdgcn_exp2f(t.y);
;     const f32x2 d = e + 1.0f; f32x2 r; r.x = __builtin_amdgcn_rcpf(d.x); r.y = __builtin_amdgcn_rcpf(d.y);
;     return (a * b) * r;
; }
;     __device__ __forceinline__ void operator()(const f32x4 (&acc)[2][2][4][2], const Unit& u, int wr, int wc, int fr, int fq, PG8_LAS unsigned char* sl) const {
;     ...
;             for (int m = 0; m < 4; ++m) { const int row = row0 + ai * HALF + m * 16; bf16_t* rowp = O + (size_t)row * ldc + col0;
;                 const float rs = __builtin_amdgcn_rsqf(sf[ai * 64 + m * 16 + fr] * (1.0f / 2048.0f) + 1e-6f);
;                 const f32x4 a0 = acc[ai][0][m][0] * rs + bw[0][0], a1 = acc[ai][0][m][1] * rs + bw[0][1], b0 = acc[ai][1][m][0] * rs + bw[1][0], b1 = acc[ai][1][m][1] * rs + bw[1][1];
;                 const f32x2 s0 = silu_mul_pk((f32x2){a0[0], a0[1]}, (f32x2){b0[0], b0[1]}), s1 = silu_mul_pk((f32x2){a0[2], a0[3]}, (f32x2){b0[2], b0[3]});
;                 const f32x2 s2 = silu_mul_pk((f32x2){a1[0], a1[1]}, (f32x2){b1[0], b1[1]}), s3 = silu_mul_pk((f32x2){a1[2], a1[3]}, (f32x2){b1[2], b1[3]});
;                 u32x4 w; w.x = cvt_pk_bf16(s0.x, s0.y); w.y = cvt_pk_bf16(s1.x, s1.y); w.z = cvt_pk_bf16(s2.x, s2.y); w.w = cvt_pk_bf16(s3.x, s3.y);
;                 *(u32x4*)rowp = w; }
.LBB0_271:
	ds_read_b32 v128, v163
	ds_read_b128 v[144:147], v162 offset:512
	v_lshl_or_b32 v168, s74, 7, v164
	v_add_u32_e32 v166, s22, v160
	v_ashrrev_i32_e32 v169, 31, v168
	s_waitcnt lgkmcnt(0)
	v_fmamk_f32 v128, v128, 0x3a000000, v233
	v_rsq_f32_e32 v170, v128
	ds_read_b128 v[140:143], v162 offset:528
	ds_read_b128 v[132:135], v162 offset:640
	ds_read_b128 v[128:131], v162 offset:656
	s_andn2_b64 vcc, exec, s[6:7]
	s_mov_b64 s[6:7], -1
	v_pk_fma_f32 v[138:139], v[138:139], v[170:171], v[146:147] op_sel_hi:[1,0,1]
	v_pk_fma_f32 v[136:137], v[136:137], v[170:171], v[144:145] op_sel_hi:[1,0,1]
	s_waitcnt lgkmcnt(0)
	v_pk_fma_f32 v[126:127], v[126:127], v[170:171], v[142:143] op_sel_hi:[1,0,1]
	v_pk_fma_f32 v[122:123], v[122:123], v[170:171], v[134:135] op_sel_hi:[1,0,1]
	v_pk_fma_f32 v[124:125], v[124:125], v[170:171], v[140:141] op_sel_hi:[1,0,1]
	v_pk_fma_f32 v[120:121], v[120:121], v[170:171], v[132:133] op_sel_hi:[1,0,1]
	v_pk_fma_f32 v[116:117], v[116:117], v[170:171], v[128:129] op_sel_hi:[1,0,1]
	v_pk_fma_f32 v[118:119], v[118:119], v[170:171], v[130:131] op_sel_hi:[1,0,1]
	v_pk_mul_f32 v[170:171], v[136:137], s[72:73] op_sel_hi:[1,0]
	v_pk_mul_f32 v[172:173], v[138:139], s[72:73] op_sel_hi:[1,0]
	v_pk_mul_f32 v[122:123], v[138:139], v[122:123]
	v_pk_mul_f32 v[138:139], v[126:127], s[72:73] op_sel_hi:[1,0]
	v_exp_f32_e32 v170, v170
	v_exp_f32_e32 v171, v171
	v_exp_f32_e32 v172, v172
	v_exp_f32_e32 v173, v173
	v_pk_mul_f32 v[120:121], v[136:137], v[120:121]
	v_pk_mul_f32 v[136:137], v[124:125], s[72:73] op_sel_hi:[1,0]
	v_exp_f32_e32 v138, v138
	v_exp_f32_e32 v139, v139
	v_exp_f32_e32 v136, v136
	v_exp_f32_e32 v137, v137
	v_pk_add_f32 v[170:171], v[170:171], 1.0 op_sel_hi:[1,0]
	v_pk_add_f32 v[172:173], v[172:173], 1.0 op_sel_hi:[1,0]
	v_pk_add_f32 v[138:139], v[138:139], 1.0 op_sel_hi:[1,0]
	v_rcp_f32_e32 v170, v170
	v_rcp_f32_e32 v171, v171
	v_rcp_f32_e32 v172, v172
	v_rcp_f32_e32 v173, v173
	v_pk_add_f32 v[136:137], v[136:137], 1.0 op_sel_hi:[1,0]
	v_rcp_f32_e32 v138, v138
	v_rcp_f32_e32 v139, v139
	v_rcp_f32_e32 v136, v136
	v_rcp_f32_e32 v137, v137
	v_pk_mul_f32 v[118:119], v[126:127], v[118:119]
	v_pk_mul_f32 v[120:121], v[120:121], v[170:171]
	v_pk_mul_f32 v[122:123], v[122:123], v[172:173]
	v_pk_mul_f32 v[116:117], v[124:125], v[116:117]
	v_pk_mul_f32 v[118:119], v[118:119], v[138:139]
	v_pk_mul_f32 v[116:117], v[116:117], v[136:137]
	v_cvt_pk_bf16_f32 v120, v120, v121
	v_cvt_pk_bf16_f32 v121, v122, v123
	s_nop 0
	v_cvt_pk_bf16_f32 v122, v116, v117
	v_cvt_pk_bf16_f32 v123, v118, v119
	ds_read_b32 v118, v163 offset:64
	v_mov_b64_e32 v[116:117], s[92:93]
	v_mad_i64_i32 v[124:125], s[22:23], v166, s34, v[116:117]
	s_waitcnt lgkmcnt(0)
	v_fmamk_f32 v118, v118, 0x3a000000, v233
	v_rsq_f32_e32 v126, v118
	v_lshlrev_b64 v[118:119], 1, v[168:169]
	v_lshl_add_u64 v[124:125], v[124:125], 0, v[118:119]
	global_store_dwordx4 v[124:125], v[120:123], off nt
	v_pk_fma_f32 v[112:113], v[112:113], v[126:127], v[144:145] op_sel_hi:[1,0,1]
	v_pk_fma_f32 v[114:115], v[114:115], v[126:127], v[146:147] op_sel_hi:[1,0,1]
	v_pk_fma_f32 v[110:111], v[110:111], v[126:127], v[142:143] op_sel_hi:[1,0,1]
	v_pk_fma_f32 v[108:109], v[108:109], v[126:127], v[140:141] op_sel_hi:[1,0,1]
	v_pk_fma_f32 v[104:105], v[104:105], v[126:127], v[132:133] op_sel_hi:[1,0,1]
	v_pk_fma_f32 v[106:107], v[106:107], v[126:127], v[134:135] op_sel_hi:[1,0,1]
	v_pk_mul_f32 v[120:121], v[112:113], s[72:73] op_sel_hi:[1,0]
	v_pk_mul_f32 v[122:123], v[114:115], s[72:73] op_sel_hi:[1,0]
	v_exp_f32_e32 v120, v120
	v_exp_f32_e32 v121, v121
	v_pk_mul_f32 v[106:107], v[114:115], v[106:107]
	v_pk_mul_f32 v[104:105], v[112:113], v[104:105]
	v_pk_mul_f32 v[112:113], v[108:109], s[72:73] op_sel_hi:[1,0]
	v_pk_mul_f32 v[114:115], v[110:111], s[72:73] op_sel_hi:[1,0]
	v_exp_f32_e32 v122, v122
	v_exp_f32_e32 v123, v123
	v_exp_f32_e32 v112, v112
	v_exp_f32_e32 v113, v113
	v_exp_f32_e32 v114, v114
	v_exp_f32_e32 v115, v115
	v_pk_add_f32 v[120:121], v[120:121], 1.0 op_sel_hi:[1,0]
	v_pk_add_f32 v[122:123], v[122:123], 1.0 op_sel_hi:[1,0]
	v_rcp_f32_e32 v120, v120
	v_rcp_f32_e32 v121, v121
	v_pk_add_f32 v[112:113], v[112:113], 1.0 op_sel_hi:[1,0]
	v_pk_add_f32 v[114:115], v[114:115], 1.0 op_sel_hi:[1,0]
	v_rcp_f32_e32 v122, v122
	v_rcp_f32_e32 v123, v123
	v_rcp_f32_e32 v112, v112
	v_rcp_f32_e32 v113, v113
	v_rcp_f32_e32 v114, v114
	v_rcp_f32_e32 v115, v115
	v_pk_fma_f32 v[100:101], v[100:101], v[126:127], v[128:129] op_sel_hi:[1,0,1]
	v_pk_fma_f32 v[102:103], v[102:103], v[126:127], v[130:131] op_sel_hi:[1,0,1]
	v_pk_mul_f32 v[104:105], v[104:105], v[120:121]
	v_pk_mul_f32 v[102:103], v[110:111], v[102:103]
	v_pk_mul_f32 v[100:101], v[108:109], v[100:101]
	v_pk_mul_f32 v[106:107], v[106:107], v[122:123]
	v_pk_mul_f32 v[108:109], v[100:101], v[112:113]
	v_pk_mul_f32 v[110:111], v[102:103], v[114:115]
	v_cvt_pk_bf16_f32 v100, v104, v105
	v_cvt_pk_bf16_f32 v101, v106, v107
	v_cvt_pk_bf16_f32 v102, v108, v109
	v_or_b32_e32 v105, 16, v166
	v_cvt_pk_bf16_f32 v103, v110, v111
	ds_read_b32 v104, v163 offset:128
	v_mad_i64_i32 v[106:107], s[22:23], v105, s34, v[116:117]
	v_lshl_add_u64 v[106:107], v[106:107], 0, v[118:119]
	global_store_dwordx4 v[106:107], v[100:103], off nt
	s_waitcnt lgkmcnt(0)
; __device__ __forceinline__ unsigned cvt_pk_bf16(float lo, float hi) { unsigned r; asm volatile("v_cvt_pk_bf16_f32 %0, %1, %2" : "=v"(r) : "v"(lo), "v"(hi)); return r; }
;     __device__ __forceinline__ void operator()(const f32x4 (&acc)[2][2][4][2], const Unit& u, int wr, int wc, int fr, int fq, PG8_LAS unsigned char* sl) const {
;     ...
;             for (int m = 0; m < 4; ++m) { const int row = row0 + ai * HALF + m * 16; bf16_t* rowp = O + (size_t)row * ldc + col0;
;                 const float rs = __builtin_amdgcn_rsqf(sf[ai * 64 + m * 16 + fr] * (1.0f / 2048.0f) + 1e-6f);
;                 const f32x4 a0 = acc[ai][0][m][0] * rs + bw[0][0], a1 = acc[ai][0][m][1] * rs + bw[0][1], b0 = acc[ai][1][m][0] * rs + bw[1][0], b1 = acc[ai][1][m][1] * rs + bw[1][1];
;                 const f32x2 s0 = silu_mul_pk((f32x2){a0[0], a0[1]}, (f32x2){b0[0], b0[1]}), s1 = silu_mul_pk((f32x2){a0[2], a0[3]}, (f32x2){b0[2], b0[3]});
;                 const f32x2 s2 = silu_mul_pk((f32x2){a1[0], a1[1]}, (f32x2){b1[0], b1[1]}), s3 = silu_mul_pk((f32x2){a1[2], a1[3]}, (f32x2){b1[2], b1[3]});
;                 u32x4 w; w.x = cvt_pk_bf16(s0.x, s0.y); w.y = cvt_pk_bf16(s1.x, s1.y); w.z = cvt_pk_bf16(s2.x, s2.y); w.w = cvt_pk_bf16(s3.x, s3.y);
;                 *(u32x4*)rowp = w; }
	v_fmamk_f32 v104, v104, 0x3a000000, v233
	v_rsq_f32_e32 v104, v104
	s_nop 0
	v_pk_fma_f32 v[96:97], v[96:97], v[104:105], v[144:145] op_sel_hi:[1,0,1]
	v_pk_fma_f32 v[98:99], v[98:99], v[104:105], v[146:147] op_sel_hi:[1,0,1]
	v_pk_fma_f32 v[94:95], v[94:95], v[104:105], v[142:143] op_sel_hi:[1,0,1]
	v_pk_fma_f32 v[92:93], v[92:93], v[104:105], v[140:141] op_sel_hi:[1,0,1]
	v_pk_fma_f32 v[88:89], v[88:89], v[104:105], v[132:133] op_sel_hi:[1,0,1]
	v_pk_fma_f32 v[90:91], v[90:91], v[104:105], v[134:135] op_sel_hi:[1,0,1]
	v_pk_mul_f32 v[100:101], v[96:97], s[72:73] op_sel_hi:[1,0]
	v_pk_mul_f32 v[102:103], v[98:99], s[72:73] op_sel_hi:[1,0]
	v_exp_f32_e32 v100, v100
	v_exp_f32_e32 v101, v101
	v_pk_mul_f32 v[90:91], v[98:99], v[90:91]
	v_pk_mul_f32 v[88:89], v[96:97], v[88:89]
	v_pk_mul_f32 v[96:97], v[92:93], s[72:73] op_sel_hi:[1,0]
	v_pk_mul_f32 v[98:99], v[94:95], s[72:73] op_sel_hi:[1,0]
	v_exp_f32_e32 v102, v102
	v_exp_f32_e32 v103, v103
	v_exp_f32_e32 v96, v96
	v_exp_f32_e32 v97, v97
	v_exp_f32_e32 v98, v98
	v_exp_f32_e32 v99, v99
	v_pk_add_f32 v[100:101], v[100:101], 1.0 op_sel_hi:[1,0]
	v_pk_add_f32 v[102:103], v[102:103], 1.0 op_sel_hi:[1,0]
	v_rcp_f32_e32 v100, v100
	v_rcp_f32_e32 v101, v101
	v_pk_add_f32 v[96:97], v[96:97], 1.0 op_sel_hi:[1,0]
	v_pk_add_f32 v[98:99], v[98:99], 1.0 op_sel_hi:[1,0]
	v_rcp_f32_e32 v102, v102
	v_rcp_f32_e32 v103, v103
	v_rcp_f32_e32 v96, v96
	v_rcp_f32_e32 v97, v97
	v_rcp_f32_e32 v98, v98
	v_rcp_f32_e32 v99, v99
	v_pk_fma_f32 v[84:85], v[84:85], v[104:105], v[128:129] op_sel_hi:[1,0,1]
	v_pk_fma_f32 v[86:87], v[86:87], v[104:105], v[130:131] op_sel_hi:[1,0,1]
	v_pk_mul_f32 v[88:89], v[88:89], v[100:101]
	v_pk_mul_f32 v[86:87], v[94:95], v[86:87]
	v_pk_mul_f32 v[84:85], v[92:93], v[84:85]
	v_pk_mul_f32 v[90:91], v[90:91], v[102:103]
	v_pk_mul_f32 v[92:93], v[84:85], v[96:97]
	v_pk_mul_f32 v[94:95], v[86:87], v[98:99]
	v_cvt_pk_bf16_f32 v84, v88, v89
	v_cvt_pk_bf16_f32 v85, v90, v91
	v_cvt_pk_bf16_f32 v86, v92, v93
	v_or_b32_e32 v89, 32, v166
	v_cvt_pk_bf16_f32 v87, v94, v95
	ds_read_b32 v88, v163 offset:192
	v_mad_i64_i32 v[90:91], s[22:23], v89, s34, v[116:117]
	v_lshl_add_u64 v[90:91], v[90:91], 0, v[118:119]
	global_store_dwordx4 v[90:91], v[84:87], off nt
	s_waitcnt lgkmcnt(0)
	v_fmamk_f32 v88, v88, 0x3a000000, v233
	v_rsq_f32_e32 v88, v88
	s_nop 0
	v_pk_fma_f32 v[80:81], v[80:81], v[88:89], v[144:145] op_sel_hi:[1,0,1]
	v_pk_fma_f32 v[82:83], v[82:83], v[88:89], v[146:147] op_sel_hi:[1,0,1]
	v_pk_fma_f32 v[78:79], v[78:79], v[88:89], v[142:143] op_sel_hi:[1,0,1]
	v_pk_fma_f32 v[76:77], v[76:77], v[88:89], v[140:141] op_sel_hi:[1,0,1]
	v_pk_fma_f32 v[72:73], v[72:73], v[88:89], v[132:133] op_sel_hi:[1,0,1]
	v_pk_fma_f32 v[74:75], v[74:75], v[88:89], v[134:135] op_sel_hi:[1,0,1]
	v_pk_mul_f32 v[84:85], v[80:81], s[72:73] op_sel_hi:[1,0]
	v_pk_mul_f32 v[86:87], v[82:83], s[72:73] op_sel_hi:[1,0]
	v_exp_f32_e32 v84, v84
	v_exp_f32_e32 v85, v85
	v_pk_mul_f32 v[74:75], v[82:83], v[74:75]
	v_pk_mul_f32 v[72:73], v[80:81], v[72:73]
	v_pk_mul_f32 v[80:81], v[76:77], s[72:73] op_sel_hi:[1,0]
	v_pk_mul_f32 v[82:83], v[78:79], s[72:73] op_sel_hi:[1,0]
	v_exp_f32_e32 v86, v86
	v_exp_f32_e32 v87, v87
	v_exp_f32_e32 v80, v80
	v_exp_f32_e32 v81, v81
	v_exp_f32_e32 v82, v82
	v_exp_f32_e32 v83, v83
	v_pk_add_f32 v[84:85], v[84:85], 1.0 op_sel_hi:[1,0]
	v_pk_add_f32 v[86:87], v[86:87], 1.0 op_sel_hi:[1,0]
	v_rcp_f32_e32 v84, v84
	v_rcp_f32_e32 v85, v85
	v_pk_add_f32 v[80:81], v[80:81], 1.0 op_sel_hi:[1,0]
	v_pk_add_f32 v[82:83], v[82:83], 1.0 op_sel_hi:[1,0]
	v_rcp_f32_e32 v86, v86
	v_rcp_f32_e32 v87, v87
	v_rcp_f32_e32 v80, v80
	v_rcp_f32_e32 v81, v81
	v_rcp_f32_e32 v82, v82
	v_rcp_f32_e32 v83, v83
	v_pk_fma_f32 v[68:69], v[68:69], v[88:89], v[128:129] op_sel_hi:[1,0,1]
	v_pk_fma_f32 v[70:71], v[70:71], v[88:89], v[130:131] op_sel_hi:[1,0,1]
	v_pk_mul_f32 v[72:73], v[72:73], v[84:85]
	v_pk_mul_f32 v[70:71], v[78:79], v[70:71]
	v_pk_mul_f32 v[68:69], v[76:77], v[68:69]
	v_pk_mul_f32 v[74:75], v[74:75], v[86:87]
	v_pk_mul_f32 v[76:77], v[68:69], v[80:81]
	v_pk_mul_f32 v[78:79], v[70:71], v[82:83]
	v_cvt_pk_bf16_f32 v68, v72, v73
	v_cvt_pk_bf16_f32 v69, v74, v75
	v_cvt_pk_bf16_f32 v70, v76, v77
	v_or_b32_e32 v73, 48, v166
	v_cvt_pk_bf16_f32 v71, v78, v79
	ds_read_b32 v72, v163 offset:256
	v_mad_i64_i32 v[74:75], s[22:23], v73, s34, v[116:117]
	v_lshl_add_u64 v[74:75], v[74:75], 0, v[118:119]
	global_store_dwordx4 v[74:75], v[68:71], off nt
	s_waitcnt lgkmcnt(0)
	v_fmamk_f32 v72, v72, 0x3a000000, v233
	v_rsq_f32_e32 v72, v72
	s_nop 0
	v_pk_fma_f32 v[64:65], v[64:65], v[72:73], v[144:145] op_sel_hi:[1,0,1]
	v_pk_fma_f32 v[66:67], v[66:67], v[72:73], v[146:147] op_sel_hi:[1,0,1]
	v_pk_fma_f32 v[62:63], v[62:63], v[72:73], v[142:143] op_sel_hi:[1,0,1]
	v_pk_fma_f32 v[60:61], v[60:61], v[72:73], v[140:141] op_sel_hi:[1,0,1]
	v_pk_fma_f32 v[56:57], v[56:57], v[72:73], v[132:133] op_sel_hi:[1,0,1]
	v_pk_fma_f32 v[58:59], v[58:59], v[72:73], v[134:135] op_sel_hi:[1,0,1]
	v_pk_mul_f32 v[68:69], v[64:65], s[72:73] op_sel_hi:[1,0]
	v_pk_mul_f32 v[70:71], v[66:67], s[72:73] op_sel_hi:[1,0]
	v_exp_f32_e32 v68, v68
	v_exp_f32_e32 v69, v69
	v_pk_mul_f32 v[58:59], v[66:67], v[58:59]
	v_pk_mul_f32 v[56:57], v[64:65], v[56:57]
	v_pk_mul_f32 v[64:65], v[60:61], s[72:73] op_sel_hi:[1,0]
	v_pk_mul_f32 v[66:67], v[62:63], s[72:73] op_sel_hi:[1,0]
	v_exp_f32_e32 v70, v70
	v_exp_f32_e32 v71, v71
	v_exp_f32_e32 v64, v64
	v_exp_f32_e32 v65, v65
	v_exp_f32_e32 v66, v66
	v_exp_f32_e32 v67, v67
	v_pk_add_f32 v[68:69], v[68:69], 1.0 op_sel_hi:[1,0]
	v_pk_add_f32 v[70:71], v[70:71], 1.0 op_sel_hi:[1,0]
	v_rcp_f32_e32 v68, v68
	v_rcp_f32_e32 v69, v69
	v_pk_add_f32 v[64:65], v[64:65], 1.0 op_sel_hi:[1,0]
	v_pk_add_f32 v[66:67], v[66:67], 1.0 op_sel_hi:[1,0]
	v_rcp_f32_e32 v70, v70
	v_rcp_f32_e32 v71, v71
	v_rcp_f32_e32 v64, v64
	v_rcp_f32_e32 v65, v65
	v_rcp_f32_e32 v66, v66
	v_rcp_f32_e32 v67, v67
	v_pk_fma_f32 v[52:53], v[52:53], v[72:73], v[128:129] op_sel_hi:[1,0,1]
	v_pk_fma_f32 v[54:55], v[54:55], v[72:73], v[130:131] op_sel_hi:[1,0,1]
	v_pk_mul_f32 v[56:57], v[56:57], v[68:69]
	v_pk_mul_f32 v[54:55], v[62:63], v[54:55]
	v_pk_mul_f32 v[52:53], v[60:61], v[52:53]
	v_pk_mul_f32 v[58:59], v[58:59], v[70:71]
	v_pk_mul_f32 v[60:61], v[52:53], v[64:65]
	v_pk_mul_f32 v[62:63], v[54:55], v[66:67]
	v_cvt_pk_bf16_f32 v52, v56, v57
	v_cvt_pk_bf16_f32 v53, v58, v59
	v_cvt_pk_bf16_f32 v54, v60, v61
	v_add_u32_e32 v57, 0x80, v166
	v_cvt_pk_bf16_f32 v55, v62, v63
	ds_read_b32 v56, v163 offset:320
	v_mad_i64_i32 v[58:59], s[22:23], v57, s34, v[116:117]
	v_lshl_add_u64 v[58:59], v[58:59], 0, v[118:119]
	global_store_dwordx4 v[58:59], v[52:55], off nt
	s_waitcnt lgkmcnt(0)
; __device__ __forceinline__ unsigned cvt_pk_bf16(float lo, float hi) { unsigned r; asm volatile("v_cvt_pk_bf16_f32 %0, %1, %2" : "=v"(r) : "v"(lo), "v"(hi)); return r; }
; #define PG8_BAR __builtin_amdgcn_s_barrier()
;     __device__ __forceinline__ void operator()(const f32x4 (&acc)[2][2][4][2], const Unit& u, int wr, int wc, int fr, int fq, PG8_LAS unsigned char* sl) const {
;     ...
;             for (int m = 0; m < 4; ++m) { const int row = row0 + ai * HALF + m * 16; bf16_t* rowp = O + (size_t)row * ldc + col0;
;                 const float rs = __builtin_amdgcn_rsqf(sf[ai * 64 + m * 16 + fr] * (1.0f / 2048.0f) + 1e-6f);
;                 const f32x4 a0 = acc[ai][0][m][0] * rs + bw[0][0], a1 = acc[ai][0][m][1] * rs + bw[0][1], b0 = acc[ai][1][m][0] * rs + bw[1][0], b1 = acc[ai][1][m][1] * rs + bw[1][1];
;                 const f32x2 s0 = silu_mul_pk((f32x2){a0[0], a0[1]}, (f32x2){b0[0], b0[1]}), s1 = silu_mul_pk((f32x2){a0[2], a0[3]}, (f32x2){b0[2], b0[3]});
;                 const f32x2 s2 = silu_mul_pk((f32x2){a1[0], a1[1]}, (f32x2){b1[0], b1[1]}), s3 = silu_mul_pk((f32x2){a1[2], a1[3]}, (f32x2){b1[2], b1[3]});
;                 u32x4 w; w.x = cvt_pk_bf16(s0.x, s0.y); w.y = cvt_pk_bf16(s1.x, s1.y); w.z = cvt_pk_bf16(s2.x, s2.y); w.w = cvt_pk_bf16(s3.x, s3.y);
;                 *(u32x4*)rowp = w; }
; template <class Epi, class Sched, bool ALIGN_EPI = false, bool SP2 = false>
; __device__ __forceinline__ void gemm_phase(PG8_LAS unsigned char* lds, const Gemm g, const Sched& S, const Epi& E, const int tid) {
;     ...
;         if (!has_next) break;
; #pragma unroll
;         for (int a = 0; a < 2; ++a)
; #pragma unroll
;             for (int b = 0; b < 2; ++b)
; #pragma unroll
;                 for (int m = 0; m < 4; ++m)
; #pragma unroll
;                     for (int n = 0; n < 2; ++n) acc[a][b][m][n] = (f32x4){0.f, 0.f, 0.f, 0.f};
;         cur = nxt; cA = nA; cB = nB; ++ui;
;         if constexpr (ALIGN_EPI) { if (wr == 1) PG8_BAR; }
	v_fmamk_f32 v56, v56, 0x3a000000, v233
	v_rsq_f32_e32 v56, v56
	s_nop 0
	v_pk_fma_f32 v[48:49], v[48:49], v[56:57], v[144:145] op_sel_hi:[1,0,1]
	v_pk_fma_f32 v[50:51], v[50:51], v[56:57], v[146:147] op_sel_hi:[1,0,1]
	v_pk_fma_f32 v[46:47], v[46:47], v[56:57], v[142:143] op_sel_hi:[1,0,1]
	v_pk_fma_f32 v[44:45], v[44:45], v[56:57], v[140:141] op_sel_hi:[1,0,1]
	v_pk_fma_f32 v[40:41], v[40:41], v[56:57], v[132:133] op_sel_hi:[1,0,1]
	v_pk_fma_f32 v[42:43], v[42:43], v[56:57], v[134:135] op_sel_hi:[1,0,1]
	v_pk_mul_f32 v[52:53], v[48:49], s[72:73] op_sel_hi:[1,0]
	v_pk_mul_f32 v[54:55], v[50:51], s[72:73] op_sel_hi:[1,0]
	v_exp_f32_e32 v52, v52
	v_exp_f32_e32 v53, v53
	v_pk_mul_f32 v[42:43], v[50:51], v[42:43]
	v_pk_mul_f32 v[40:41], v[48:49], v[40:41]
	v_pk_mul_f32 v[48:49], v[44:45], s[72:73] op_sel_hi:[1,0]
	v_pk_mul_f32 v[50:51], v[46:47], s[72:73] op_sel_hi:[1,0]
	v_exp_f32_e32 v54, v54
	v_exp_f32_e32 v55, v55
	v_exp_f32_e32 v48, v48
	v_exp_f32_e32 v49, v49
	v_exp_f32_e32 v50, v50
	v_exp_f32_e32 v51, v51
	v_pk_add_f32 v[52:53], v[52:53], 1.0 op_sel_hi:[1,0]
	v_pk_add_f32 v[54:55], v[54:55], 1.0 op_sel_hi:[1,0]
	v_rcp_f32_e32 v52, v52
	v_rcp_f32_e32 v53, v53
	v_pk_add_f32 v[48:49], v[48:49], 1.0 op_sel_hi:[1,0]
	v_pk_add_f32 v[50:51], v[50:51], 1.0 op_sel_hi:[1,0]
	v_rcp_f32_e32 v54, v54
	v_rcp_f32_e32 v55, v55
	v_rcp_f32_e32 v48, v48
	v_rcp_f32_e32 v49, v49
	v_rcp_f32_e32 v50, v50
	v_rcp_f32_e32 v51, v51
	v_pk_fma_f32 v[36:37], v[36:37], v[56:57], v[128:129] op_sel_hi:[1,0,1]
	v_pk_fma_f32 v[38:39], v[38:39], v[56:57], v[130:131] op_sel_hi:[1,0,1]
	v_pk_mul_f32 v[40:41], v[40:41], v[52:53]
	v_pk_mul_f32 v[38:39], v[46:47], v[38:39]
	v_pk_mul_f32 v[36:37], v[44:45], v[36:37]
	v_pk_mul_f32 v[42:43], v[42:43], v[54:55]
	v_pk_mul_f32 v[44:45], v[36:37], v[48:49]
	v_pk_mul_f32 v[46:47], v[38:39], v[50:51]
	v_cvt_pk_bf16_f32 v36, v40, v41
	v_cvt_pk_bf16_f32 v37, v42, v43
	v_cvt_pk_bf16_f32 v38, v44, v45
	v_add_u32_e32 v41, 0x90, v166
	v_cvt_pk_bf16_f32 v39, v46, v47
	ds_read_b32 v40, v163 offset:384
	v_mad_i64_i32 v[42:43], s[22:23], v41, s34, v[116:117]
	v_lshl_add_u64 v[42:43], v[42:43], 0, v[118:119]
	global_store_dwordx4 v[42:43], v[36:39], off nt
	s_waitcnt lgkmcnt(0)
	v_fmamk_f32 v40, v40, 0x3a000000, v233
	v_rsq_f32_e32 v40, v40
	v_add_u32_e32 v44, 0xa0, v166
	v_add_u32_e32 v45, 0xb0, v166
	v_pk_fma_f32 v[34:35], v[34:35], v[40:41], v[146:147] op_sel_hi:[1,0,1]
	v_pk_fma_f32 v[32:33], v[32:33], v[40:41], v[144:145] op_sel_hi:[1,0,1]
	v_pk_fma_f32 v[30:31], v[30:31], v[40:41], v[142:143] op_sel_hi:[1,0,1]
	v_pk_fma_f32 v[28:29], v[28:29], v[40:41], v[140:141] op_sel_hi:[1,0,1]
	v_pk_fma_f32 v[24:25], v[24:25], v[40:41], v[132:133] op_sel_hi:[1,0,1]
	v_pk_fma_f32 v[26:27], v[26:27], v[40:41], v[134:135] op_sel_hi:[1,0,1]
	v_pk_mul_f32 v[38:39], v[34:35], s[72:73] op_sel_hi:[1,0]
	v_pk_mul_f32 v[36:37], v[32:33], s[72:73] op_sel_hi:[1,0]
	v_exp_f32_e32 v38, v38
	v_exp_f32_e32 v39, v39
	v_pk_mul_f32 v[26:27], v[34:35], v[26:27]
	v_pk_mul_f32 v[24:25], v[32:33], v[24:25]
	v_pk_mul_f32 v[32:33], v[28:29], s[72:73] op_sel_hi:[1,0]
	v_pk_mul_f32 v[34:35], v[30:31], s[72:73] op_sel_hi:[1,0]
	v_exp_f32_e32 v36, v36
	v_exp_f32_e32 v37, v37
	v_exp_f32_e32 v32, v32
	v_exp_f32_e32 v33, v33
	v_exp_f32_e32 v34, v34
	v_exp_f32_e32 v35, v35
	v_pk_add_f32 v[38:39], v[38:39], 1.0 op_sel_hi:[1,0]
	v_pk_add_f32 v[36:37], v[36:37], 1.0 op_sel_hi:[1,0]
	v_rcp_f32_e32 v38, v38
	v_rcp_f32_e32 v39, v39
	v_pk_add_f32 v[32:33], v[32:33], 1.0 op_sel_hi:[1,0]
	v_pk_add_f32 v[34:35], v[34:35], 1.0 op_sel_hi:[1,0]
	v_rcp_f32_e32 v36, v36
	v_rcp_f32_e32 v37, v37
	v_rcp_f32_e32 v32, v32
	v_rcp_f32_e32 v33, v33
	v_rcp_f32_e32 v34, v34
	v_rcp_f32_e32 v35, v35
	v_pk_fma_f32 v[20:21], v[20:21], v[40:41], v[128:129] op_sel_hi:[1,0,1]
	v_pk_fma_f32 v[22:23], v[22:23], v[40:41], v[130:131] op_sel_hi:[1,0,1]
	v_pk_mul_f32 v[26:27], v[26:27], v[38:39]
	v_pk_mul_f32 v[22:23], v[30:31], v[22:23]
	v_pk_mul_f32 v[20:21], v[28:29], v[20:21]
	v_pk_mul_f32 v[24:25], v[24:25], v[36:37]
	v_pk_mul_f32 v[28:29], v[20:21], v[32:33]
	v_pk_mul_f32 v[30:31], v[22:23], v[34:35]
	v_cvt_pk_bf16_f32 v20, v24, v25
	v_cvt_pk_bf16_f32 v21, v26, v27
	v_cvt_pk_bf16_f32 v22, v28, v29
	v_mad_i64_i32 v[24:25], s[22:23], v44, s34, v[116:117]
	v_cvt_pk_bf16_f32 v23, v30, v31
	ds_read_b32 v26, v163 offset:448
	v_lshl_add_u64 v[24:25], v[24:25], 0, v[118:119]
	global_store_dwordx4 v[24:25], v[20:23], off nt
	s_waitcnt lgkmcnt(0)
	s_nop 0
	v_fmamk_f32 v20, v26, 0x3a000000, v233
	v_rsq_f32_e32 v20, v20
	v_mad_i64_i32 v[22:23], s[22:23], v45, s34, v[116:117]
	v_lshl_add_u64 v[22:23], v[22:23], 0, v[118:119]
	v_pk_fma_f32 v[18:19], v[18:19], v[20:21], v[146:147] op_sel_hi:[1,0,1]
	v_pk_fma_f32 v[16:17], v[16:17], v[20:21], v[144:145] op_sel_hi:[1,0,1]
	v_pk_fma_f32 v[14:15], v[14:15], v[20:21], v[142:143] op_sel_hi:[1,0,1]
	v_pk_fma_f32 v[12:13], v[12:13], v[20:21], v[140:141] op_sel_hi:[1,0,1]
	v_pk_fma_f32 v[8:9], v[8:9], v[20:21], v[132:133] op_sel_hi:[1,0,1]
	v_pk_fma_f32 v[10:11], v[10:11], v[20:21], v[134:135] op_sel_hi:[1,0,1]
	v_pk_fma_f32 v[4:5], v[4:5], v[20:21], v[128:129] op_sel_hi:[1,0,1]
	v_pk_fma_f32 v[6:7], v[6:7], v[20:21], v[130:131] op_sel_hi:[1,0,1]
	v_pk_mul_f32 v[20:21], v[16:17], s[72:73] op_sel_hi:[1,0]
	v_pk_mul_f32 v[24:25], v[18:19], s[72:73] op_sel_hi:[1,0]
	v_pk_mul_f32 v[10:11], v[18:19], v[10:11]
	v_pk_mul_f32 v[8:9], v[16:17], v[8:9]
	v_pk_mul_f32 v[16:17], v[12:13], s[72:73] op_sel_hi:[1,0]
	v_pk_mul_f32 v[18:19], v[14:15], s[72:73] op_sel_hi:[1,0]
	v_exp_f32_e32 v20, v20
	v_exp_f32_e32 v21, v21
	v_exp_f32_e32 v24, v24
	v_exp_f32_e32 v25, v25
	v_exp_f32_e32 v16, v16
	v_exp_f32_e32 v17, v17
	v_exp_f32_e32 v18, v18
	v_exp_f32_e32 v19, v19
	v_pk_add_f32 v[20:21], v[20:21], 1.0 op_sel_hi:[1,0]
	v_pk_add_f32 v[24:25], v[24:25], 1.0 op_sel_hi:[1,0]
	v_pk_add_f32 v[16:17], v[16:17], 1.0 op_sel_hi:[1,0]
	v_pk_add_f32 v[18:19], v[18:19], 1.0 op_sel_hi:[1,0]
	v_rcp_f32_e32 v20, v20
	v_rcp_f32_e32 v21, v21
	v_rcp_f32_e32 v24, v24
	v_rcp_f32_e32 v25, v25
	v_rcp_f32_e32 v16, v16
	v_rcp_f32_e32 v17, v17
	v_rcp_f32_e32 v18, v18
	v_rcp_f32_e32 v19, v19
	v_pk_mul_f32 v[6:7], v[14:15], v[6:7]
	v_pk_mul_f32 v[4:5], v[12:13], v[4:5]
	v_pk_mul_f32 v[8:9], v[8:9], v[20:21]
	v_pk_mul_f32 v[10:11], v[10:11], v[24:25]
	v_pk_mul_f32 v[12:13], v[4:5], v[16:17]
	v_pk_mul_f32 v[14:15], v[6:7], v[18:19]
	v_cvt_pk_bf16_f32 v4, v8, v9
	v_cvt_pk_bf16_f32 v5, v10, v11
	v_cvt_pk_bf16_f32 v6, v12, v13
	s_nop 0
	v_cvt_pk_bf16_f32 v7, v14, v15
	global_store_dwordx4 v[22:23], v[4:7], off nt
	s_cbranch_vccnz .LBB0_262
	s_andn2_b64 vcc, exec, s[10:11]
	s_cbranch_vccnz .LBB0_261
	s_barrier
	s_branch .LBB0_261
